# ret_unit_c: the head's group-norm weight vector loaded once before the four-unit loop instead of four serialized load pairs inside every unit
# baseline (speedup 1.0000x reference)
; __device__ __forceinline__ unsigned cvt_pk_bf16(float lo, float hi) { const f32x2_t v = {lo, hi}; const bf16x2_t b = __builtin_convertvector(v, bf16x2_t); return __builtin_bit_cast(unsigned, b); }
; #define LAS __attribute__((address_space(3)))
; template <bool WITH_K>
; __device__ __forceinline__ void ret_load_qk(PR P, LAS bf16_t* QP, LAS bf16_t* KB, unsigned (&kth)[4][4], const int tidv, const int row0, const int n, const int h, const float kd0, const float g32) {
;     const bf16_t* PS = (const bf16_t*)(P.ws + WS_BIG); const float* rc = (const float*)(P.ws + WS_ROPE); const float* rs = rc + 2052 * 64;
;     float kd = kd0;
; #pragma unroll
;     for (int it = 0; it < 4; ++it) { const int idx = it * 512 + tidv, i = idx >> 4, f = (idx & 15) * 4;
;         const bf16_t* src = PS + (size_t)(row0 + i) * NCOLS + 1792 + h * 128;
;         const u32x2 q1 = *(const u32x2*)(src + f), q2 = *(const u32x2*)(src + 64 + f);
;         u32x2 k1 = (u32x2){0u, 0u}, k2 = k1; if (WITH_K) { k1 = *(const u32x2*)(src + 512 + f); k2 = *(const u32x2*)(src + 576 + f); }
;         const float4 cs = *(const float4*)(rc + (size_t)(n * 128 + i) * 64 + f), sn = *(const float4*)(rs + (size_t)(n * 128 + i) * 64 + f);
;         const float c4[4] = {cs.x, cs.y, cs.z, cs.w}, s4[4] = {sn.x, sn.y, sn.z, sn.w};
;         const float qa[4] = {lo_bf(q1.x), hi_bf(q1.x), lo_bf(q1.y), hi_bf(q1.y)}, qb[4] = {lo_bf(q2.x), hi_bf(q2.x), lo_bf(q2.y), hi_bf(q2.y)};
;         float qo1[4], qo2[4];
; #pragma unroll
;         for (int x = 0; x < 4; ++x) { qo1[x] = qa[x] * c4[x] - qb[x] * s4[x]; qo2[x] = qa[x] * s4[x] + qb[x] * c4[x]; }
;         u32x2 w; w.x = pg8::cvt_pk_bf16(qo1[0], qo1[1]); w.y = pg8::cvt_pk_bf16(qo1[2], qo1[3]); *(LAS u32x2*)(QP + i * RS + f) = w;
;         w.x = pg8::cvt_pk_bf16(qo2[0], qo2[1]); w.y = pg8::cvt_pk_bf16(qo2[2], qo2[3]); *(LAS u32x2*)(QP + i * RS + 64 + f) = w;
; __device__ __forceinline__ void ret_unit_c(PR P, LAS unsigned char* lds, const int bh, const int n, const int wv) {
;     ...
;       const bf16_t* gp = PS + (size_t)(row0 + i) * NCOLS + 1792 + 1536 + h * 128 + part * 32; const float* gw = P.gn_w + h * 128 + part * 32;
; #pragma unroll
;       for (int x = 0; x < 4; ++x) { const u32x4 g4 = *(const u32x4*)(gp + x * 8); const float4 w0 = *(const float4*)(gw + x * 8), w1 = *(const float4*)(gw + x * 8 + 4);
.LBB0_653:
	s_or_b64 exec, exec, s[18:19]
	s_barrier
	s_load_dwordx2 s[12:13], s[38:39], 0xa8
	s_movk_i32 s28, 0xff80
	s_mov_b32 s19, 0
	s_mov_b32 s29, 0xcb64800
	s_mov_b32 s30, 0xc2fc0000
	v_mov_b32_e32 v62, 0x42800000
	v_mov_b32_e32 v29, 0
	s_movk_i32 s31, 0x1e00
	v_mov_b64_e32 v[30:31], s[10:11]
	s_mov_b64 s[20:21], 0x3d45600
	s_mov_b32 s34, 0x3d45000
	s_movk_i32 s35, 0x110
	s_add_i32 s36, 0, 0x19800
	s_mov_b32 s37, 0x800000
	v_mov_b32_e32 v63, 0x42000000
	v_not_b32_e32 v64, 63
	s_movk_i32 s40, 0x210
	s_mov_b64 s[22:23], 0x1bc4c00
	s_mov_b32 s41, 0x1bc4000
	s_movk_i32 s42, 0x1600
	s_mov_b64 s[24:25], 0x3d46200
	s_mov_b32 s43, 0x3d46000
	v_mov_b32_e32 v65, 0x3727c5ac
	s_waitcnt lgkmcnt(0)
	s_add_i32 s98, s2, 0xffffff80
	s_ashr_i32 s98, s98, 4
	s_and_b32 s98, s98, 3
	s_lshl_b32 s98, s98, 9
	s_add_u32 s98, s12, s98
	s_addc_u32 s99, s13, 0
	v_mbcnt_lo_u32_b32 v190, -1, 0
	v_mbcnt_hi_u32_b32 v190, -1, v190
	v_and_b32_e32 v190, 3, v190
	v_lshlrev_b32_e32 v190, 7, v190
	global_load_dwordx4 v[228:231], v190, s[98:99]
	global_load_dwordx4 v[232:235], v190, s[98:99] offset:16
	global_load_dwordx4 v[236:239], v190, s[98:99] offset:32
	global_load_dwordx4 v[240:243], v190, s[98:99] offset:48
	global_load_dwordx4 v[244:247], v190, s[98:99] offset:64
	global_load_dwordx4 v[248:251], v190, s[98:99] offset:80
	global_load_dwordx4 v[192:195], v190, s[98:99] offset:96
	global_load_dwordx4 v[196:199], v190, s[98:99] offset:112
.LBB0_654:
	s_add_i32 s18, s2, s28
	s_ashr_i32 s18, s18, 4
	s_and_b32 s44, s18, 3
	s_sub_i32 s26, s18, 29
	s_ashr_i32 s27, s18, 31
	s_cmp_lt_i32 s18, 29
	s_cselect_b32 s45, s29, 0x1444800
	s_cselect_b32 s27, s27, 0
	s_cselect_b32 s26, s18, s26
	s_add_u32 s45, s10, s45
	s_addc_u32 s46, s11, 0
	s_lshl_b64 s[26:27], s[26:27], 19
	s_add_u32 s26, s45, s26
	s_addc_u32 s27, s46, s27
	v_cvt_f32_ubyte0_e32 v0, s44
	s_add_u32 s26, s26, s7
	v_sub_f32_e32 v34, 0xc0a00000, v0
	s_addc_u32 s27, s27, 0
	v_cmp_gt_f32_e32 vcc, s30, v34
	s_and_b64 s[46:47], vcc, exec
	s_cselect_b32 s55, 0xffffffc0, 0
	s_lshl_b32 s18, s18, 9
	v_mbcnt_lo_u32_b32 v2, -1, 0
	v_mbcnt_hi_u32_b32 v2, -1, v2
	s_and_b32 s18, s18, 0xfffff800
	v_add_u32_e32 v3, s33, v2
	s_or_b32 s45, s18, s6
	v_lshlrev_b32_e32 v0, 2, v2
	v_ashrrev_i32_e32 v46, 4, v3
	v_and_b32_e32 v6, 60, v0
	v_add_u32_e32 v4, s45, v46
	v_lshlrev_b32_e32 v28, 2, v6
	v_mad_i64_i32 v[4:5], s[46:47], v4, s31, v[30:31]
	s_lshl_b32 s18, s44, 8
	v_lshl_add_u64 v[0:1], s[14:15], 0, v[28:29]
	v_lshl_add_u64 v[20:21], s[16:17], 0, v[28:29]
	v_lshl_add_u64 v[4:5], v[4:5], 0, s[18:19]
	v_lshlrev_b32_e32 v28, 1, v6
	v_lshl_add_u64 v[4:5], v[4:5], 0, v[28:29]
	v_cndmask_b32_e32 v35, 0, v62, vcc
	v_lshl_add_u64 v[6:7], v[4:5], 0, s[20:21]
	v_add_co_u32_e32 v4, vcc, s34, v4
	v_add_f32_e32 v34, v34, v35
	s_nop 0
	v_addc_co_u32_e32 v5, vcc, 0, v5, vcc
	global_load_dwordx2 v[22:23], v[4:5], off offset:1536
	global_load_dwordx2 v[24:25], v[6:7], off offset:128
	v_add_u32_e32 v4, s6, v46
	v_ashrrev_i32_e32 v5, 31, v4
	v_lshlrev_b64 v[8:9], 8, v[4:5]
	v_add_u32_e32 v4, 0x200, v3
	v_ashrrev_i32_e32 v47, 4, v4
	v_add_u32_e32 v4, s45, v47
	v_mad_i64_i32 v[4:5], s[46:47], v4, s31, v[30:31]
	v_lshl_add_u64 v[4:5], v[4:5], 0, s[18:19]
	v_lshl_add_u64 v[12:13], v[4:5], 0, v[28:29]
	v_add_co_u32_e32 v4, vcc, s34, v12
	v_exp_f32_e32 v34, v34
	s_nop 0
	v_addc_co_u32_e32 v5, vcc, 0, v13, vcc
	v_lshl_add_u64 v[12:13], v[12:13], 0, s[20:21]
	global_load_dwordx2 v[26:27], v[4:5], off offset:1536
	global_load_dwordx2 v[32:33], v[12:13], off offset:128
	v_lshl_add_u64 v[4:5], v[20:21], 0, v[8:9]
	global_load_dwordx4 v[4:7], v[4:5], off
	v_lshl_add_u64 v[8:9], v[0:1], 0, v[8:9]
	v_add_u32_e32 v12, s6, v47
	global_load_dwordx4 v[8:11], v[8:9], off
	v_ashrrev_i32_e32 v13, 31, v12
	v_lshlrev_b64 v[12:13], 8, v[12:13]
	v_lshl_add_u64 v[16:17], v[0:1], 0, v[12:13]
	v_lshl_add_u64 v[12:13], v[20:21], 0, v[12:13]
	global_load_dwordx4 v[12:15], v[12:13], off
	s_nop 0
	global_load_dwordx4 v[16:19], v[16:17], off
	v_ldexp_f32 v34, v34, s55
	v_sub_f32_e32 v57, 1.0, v34
	v_mul_lo_u32 v48, v46, s35
	v_add3_u32 v44, 0, v48, v28
	v_mul_lo_u32 v49, v47, s35
	v_bfe_u32 v56, v3, 6, 1
	s_waitcnt vmcnt(7)
	v_lshlrev_b32_e32 v34, 16, v22
	v_and_b32_e32 v35, 0xffff0000, v22
	s_waitcnt vmcnt(6)
	v_lshlrev_b32_e32 v36, 16, v24
	v_and_b32_e32 v37, 0xffff0000, v24
	v_lshlrev_b32_e32 v22, 16, v23
	v_and_b32_e32 v23, 0xffff0000, v23
	v_lshlrev_b32_e32 v24, 16, v25
	v_and_b32_e32 v25, 0xffff0000, v25
	s_waitcnt vmcnt(5)
	v_lshlrev_b32_e32 v38, 16, v26
	v_and_b32_e32 v39, 0xffff0000, v26
	s_waitcnt vmcnt(3)
	v_pk_mul_f32 v[40:41], v[4:5], v[34:35]
	v_pk_mul_f32 v[4:5], v[4:5], v[36:37]
	v_pk_mul_f32 v[42:43], v[6:7], v[22:23]
	v_pk_mul_f32 v[6:7], v[6:7], v[24:25]
	s_waitcnt vmcnt(2)
	v_pk_fma_f32 v[36:37], v[8:9], v[36:37], v[40:41]
	v_pk_fma_f32 v[4:5], v[8:9], v[34:35], v[4:5] neg_lo:[0,0,1] neg_hi:[0,0,1]
	v_pk_fma_f32 v[8:9], v[10:11], v[24:25], v[42:43]
	v_pk_fma_f32 v[6:7], v[10:11], v[22:23], v[6:7] neg_lo:[0,0,1] neg_hi:[0,0,1]
	v_cvt_pk_bf16_f32 v4, v4, v5
	v_cvt_pk_bf16_f32 v5, v6, v7
	v_cvt_pk_bf16_f32 v6, v36, v37
	v_cvt_pk_bf16_f32 v7, v8, v9
	ds_write2_b64 v44, v[4:5], v[6:7] offset1:16
	v_lshlrev_b32_e32 v4, 16, v32
	v_and_b32_e32 v5, 0xffff0000, v32
	s_waitcnt vmcnt(1)
	v_pk_mul_f32 v[6:7], v[12:13], v[38:39]
	v_lshlrev_b32_e32 v8, 16, v27
	v_and_b32_e32 v9, 0xffff0000, v27
	s_waitcnt vmcnt(0)
; __device__ __forceinline__ unsigned cvt_pk_bf16(float lo, float hi) { const f32x2_t v = {lo, hi}; const bf16x2_t b = __builtin_convertvector(v, bf16x2_t); return __builtin_bit_cast(unsigned, b); }
; #define LAS __attribute__((address_space(3)))
; __device__ __forceinline__ float lo_bf(unsigned x) { return __uint_as_float(x << 16); }
; template <bool WITH_K>
; __device__ __forceinline__ void ret_load_qk(PR P, LAS bf16_t* QP, LAS bf16_t* KB, unsigned (&kth)[4][4], const int tidv, const int row0, const int n, const int h, const float kd0, const float g32) {
;     const bf16_t* PS = (const bf16_t*)(P.ws + WS_BIG); const float* rc = (const float*)(P.ws + WS_ROPE); const float* rs = rc + 2052 * 64;
;     float kd = kd0;
; #pragma unroll
;     for (int it = 0; it < 4; ++it) { const int idx = it * 512 + tidv, i = idx >> 4, f = (idx & 15) * 4;
;         const bf16_t* src = PS + (size_t)(row0 + i) * NCOLS + 1792 + h * 128;
;         const u32x2 q1 = *(const u32x2*)(src + f), q2 = *(const u32x2*)(src + 64 + f);
;         u32x2 k1 = (u32x2){0u, 0u}, k2 = k1; if (WITH_K) { k1 = *(const u32x2*)(src + 512 + f); k2 = *(const u32x2*)(src + 576 + f); }
;         const float4 cs = *(const float4*)(rc + (size_t)(n * 128 + i) * 64 + f), sn = *(const float4*)(rs + (size_t)(n * 128 + i) * 64 + f);
;         const float c4[4] = {cs.x, cs.y, cs.z, cs.w}, s4[4] = {sn.x, sn.y, sn.z, sn.w};
;         const float qa[4] = {lo_bf(q1.x), hi_bf(q1.x), lo_bf(q1.y), hi_bf(q1.y)}, qb[4] = {lo_bf(q2.x), hi_bf(q2.x), lo_bf(q2.y), hi_bf(q2.y)};
;         float qo1[4], qo2[4];
; #pragma unroll
;         for (int x = 0; x < 4; ++x) { qo1[x] = qa[x] * c4[x] - qb[x] * s4[x]; qo2[x] = qa[x] * s4[x] + qb[x] * c4[x]; }
;         u32x2 w; w.x = pg8::cvt_pk_bf16(qo1[0], qo1[1]); w.y = pg8::cvt_pk_bf16(qo1[2], qo1[3]); *(LAS u32x2*)(QP + i * RS + f) = w;
;         w.x = pg8::cvt_pk_bf16(qo2[0], qo2[1]); w.y = pg8::cvt_pk_bf16(qo2[2], qo2[3]); *(LAS u32x2*)(QP + i * RS + 64 + f) = w;
; __device__ __forceinline__ void ret_unit_c(PR P, LAS unsigned char* lds, const int bh, const int n, const int wv) {
;     ...
; #pragma unroll
;     for (int it = 0; it < 4; ++it) { const int idx = it * 512 + tid, e = idx >> 4, d8 = (idx & 15) * 8;
;         *(LAS u32x4*)(ST + e * RS + d8) = *(const u32x4*)(KVB + e * 128 + d8); }
;     __syncthreads();
	v_pk_fma_f32 v[6:7], v[16:17], v[4:5], v[6:7]
	v_pk_mul_f32 v[4:5], v[12:13], v[4:5]
	v_lshlrev_b32_e32 v10, 16, v33
	v_and_b32_e32 v11, 0xffff0000, v33
	v_pk_mul_f32 v[12:13], v[14:15], v[8:9]
	v_pk_fma_f32 v[4:5], v[16:17], v[38:39], v[4:5] neg_lo:[0,0,1] neg_hi:[0,0,1]
	v_pk_fma_f32 v[12:13], v[18:19], v[10:11], v[12:13]
	v_pk_mul_f32 v[10:11], v[14:15], v[10:11]
	v_cvt_pk_bf16_f32 v4, v4, v5
	v_pk_fma_f32 v[8:9], v[18:19], v[8:9], v[10:11] neg_lo:[0,0,1] neg_hi:[0,0,1]
	v_cvt_pk_bf16_f32 v6, v6, v7
	v_cvt_pk_bf16_f32 v5, v8, v9
	v_add3_u32 v8, 0, v49, v28
	v_cvt_pk_bf16_f32 v7, v12, v13
	ds_write2_b64 v8, v[4:5], v[6:7] offset1:16
	v_add_u32_e32 v4, 0x400, v3
	v_ashrrev_i32_e32 v50, 4, v4
	v_add_u32_e32 v4, s45, v50
	v_mad_i64_i32 v[4:5], s[46:47], v4, s31, v[30:31]
	v_lshl_add_u64 v[4:5], v[4:5], 0, s[18:19]
	v_lshl_add_u64 v[4:5], v[4:5], 0, v[28:29]
	v_lshl_add_u64 v[6:7], v[4:5], 0, s[20:21]
	v_add_co_u32_e32 v4, vcc, s34, v4
	v_mul_lo_u32 v52, v50, s35
	s_nop 0
	v_addc_co_u32_e32 v5, vcc, 0, v5, vcc
	global_load_dwordx2 v[22:23], v[4:5], off offset:1536
	global_load_dwordx2 v[24:25], v[6:7], off offset:128
	v_add_u32_e32 v4, 0x600, v3
	v_ashrrev_i32_e32 v51, 4, v4
	v_add_u32_e32 v4, s45, v51
	v_mad_i64_i32 v[4:5], s[46:47], v4, s31, v[30:31]
	v_lshl_add_u64 v[4:5], v[4:5], 0, s[18:19]
	v_lshl_add_u64 v[4:5], v[4:5], 0, v[28:29]
	v_add_co_u32_e32 v6, vcc, s34, v4
	v_add_u32_e32 v8, s6, v51
	s_nop 0
	v_addc_co_u32_e32 v7, vcc, 0, v5, vcc
	v_lshl_add_u64 v[4:5], v[4:5], 0, s[20:21]
	global_load_dwordx2 v[26:27], v[6:7], off offset:1536
	global_load_dwordx2 v[32:33], v[4:5], off offset:128
	v_add_u32_e32 v4, s6, v50
	v_ashrrev_i32_e32 v5, 31, v4
	v_lshlrev_b64 v[12:13], 8, v[4:5]
	v_ashrrev_i32_e32 v9, 31, v8
	v_lshl_add_u64 v[4:5], v[20:21], 0, v[12:13]
	v_lshlrev_b64 v[16:17], 8, v[8:9]
	global_load_dwordx4 v[4:7], v[4:5], off
	v_lshl_add_u64 v[8:9], v[20:21], 0, v[16:17]
	v_lshl_add_u64 v[12:13], v[0:1], 0, v[12:13]
	global_load_dwordx4 v[8:11], v[8:9], off
	v_lshl_add_u64 v[0:1], v[0:1], 0, v[16:17]
	global_load_dwordx4 v[12:15], v[12:13], off
	v_mul_lo_u32 v53, v51, s35
	global_load_dwordx4 v[16:19], v[0:1], off
	v_lshlrev_b32_e32 v216, 4, v2
	v_and_b32_e32 v216, 0xf0, v216
	v_mov_b32_e32 v217, 0
	v_lshl_add_u64 v[218:219], s[26:27], 0, v[216:217]
	v_lshlrev_b32_e32 v220, 7, v46
	v_ashrrev_i32_e32 v221, 31, v220
	v_lshl_add_u64 v[220:221], v[220:221], 1, v[218:219]
	v_lshlrev_b32_e32 v222, 7, v47
	v_ashrrev_i32_e32 v223, 31, v222
	v_lshl_add_u64 v[222:223], v[222:223], 1, v[218:219]
	v_lshlrev_b32_e32 v224, 7, v50
	v_ashrrev_i32_e32 v225, 31, v224
	v_lshl_add_u64 v[224:225], v[224:225], 1, v[218:219]
	v_lshlrev_b32_e32 v226, 7, v51
	v_ashrrev_i32_e32 v227, 31, v226
	v_lshl_add_u64 v[226:227], v[226:227], 1, v[218:219]
	global_load_dwordx4 v[200:203], v[220:221], off
	global_load_dwordx4 v[204:207], v[222:223], off
	global_load_dwordx4 v[208:211], v[224:225], off
	global_load_dwordx4 v[212:215], v[226:227], off
	v_add3_u32 v54, 0, v52, v28
	v_add3_u32 v28, 0, v53, v28
	s_waitcnt vmcnt(11)
	v_lshlrev_b32_e32 v0, 16, v22
	v_and_b32_e32 v1, 0xffff0000, v22
	s_waitcnt vmcnt(10)
	v_lshlrev_b32_e32 v20, 16, v24
	v_and_b32_e32 v21, 0xffff0000, v24
	v_lshlrev_b32_e32 v22, 16, v23
	v_and_b32_e32 v23, 0xffff0000, v23
	v_lshlrev_b32_e32 v24, 16, v25
	v_and_b32_e32 v25, 0xffff0000, v25
	s_waitcnt vmcnt(9)
	v_lshlrev_b32_e32 v34, 16, v26
	v_and_b32_e32 v35, 0xffff0000, v26
	s_waitcnt vmcnt(8)
	v_lshlrev_b32_e32 v36, 16, v32
	v_and_b32_e32 v37, 0xffff0000, v32
	v_lshlrev_b32_e32 v26, 16, v27
	v_and_b32_e32 v27, 0xffff0000, v27
	v_lshlrev_b32_e32 v32, 16, v33
	v_and_b32_e32 v33, 0xffff0000, v33
	s_waitcnt vmcnt(7)
	v_pk_mul_f32 v[38:39], v[4:5], v[0:1]
	v_pk_mul_f32 v[4:5], v[4:5], v[20:21]
	v_pk_mul_f32 v[40:41], v[6:7], v[22:23]
	v_pk_mul_f32 v[6:7], v[6:7], v[24:25]
	s_waitcnt vmcnt(6)
	v_pk_mul_f32 v[42:43], v[8:9], v[34:35]
	v_pk_mul_f32 v[8:9], v[8:9], v[36:37]
	v_pk_mul_f32 v[44:45], v[10:11], v[26:27]
	v_pk_mul_f32 v[10:11], v[10:11], v[32:33]
	s_waitcnt vmcnt(5)
	v_pk_fma_f32 v[20:21], v[12:13], v[20:21], v[38:39]
	v_pk_fma_f32 v[0:1], v[12:13], v[0:1], v[4:5] neg_lo:[0,0,1] neg_hi:[0,0,1]
	v_pk_fma_f32 v[4:5], v[14:15], v[24:25], v[40:41]
	v_pk_fma_f32 v[6:7], v[14:15], v[22:23], v[6:7] neg_lo:[0,0,1] neg_hi:[0,0,1]
	s_waitcnt vmcnt(4)
	v_pk_fma_f32 v[12:13], v[16:17], v[36:37], v[42:43]
	v_pk_fma_f32 v[8:9], v[16:17], v[34:35], v[8:9] neg_lo:[0,0,1] neg_hi:[0,0,1]
	v_pk_fma_f32 v[14:15], v[18:19], v[32:33], v[44:45]
	v_pk_fma_f32 v[10:11], v[18:19], v[26:27], v[10:11] neg_lo:[0,0,1] neg_hi:[0,0,1]
	v_cvt_pk_bf16_f32 v0, v0, v1
	v_cvt_pk_bf16_f32 v1, v6, v7
	v_cvt_pk_bf16_f32 v6, v20, v21
	v_cvt_pk_bf16_f32 v7, v4, v5
	v_cvt_pk_bf16_f32 v4, v8, v9
	v_cvt_pk_bf16_f32 v5, v10, v11
	v_cvt_pk_bf16_f32 v8, v12, v13
	v_cvt_pk_bf16_f32 v9, v14, v15
	ds_write2_b64 v54, v[0:1], v[6:7] offset1:16
	ds_write2_b64 v28, v[4:5], v[8:9] offset1:16
	v_lshlrev_b32_e32 v0, 4, v2
	v_and_b32_e32 v28, 0xf0, v0
	v_ashrrev_i32_e32 v66, 2, v3
	v_and_b32_e32 v1, 15, v2
	v_and_b32_e32 v3, 0xffffffe0, v66
	v_bfe_u32 v0, v2, 4, 2
	v_or_b32_e32 v23, v3, v1
	v_lshlrev_b32_e32 v20, 4, v0
	v_add_u32_e32 v22, s36, v28
	v_mul_lo_u32 v23, v23, s35
	v_add_u32_e32 v24, v22, v48
	v_add3_u32 v28, 0, v20, v23
	v_add_u32_e32 v25, v22, v49
	v_add_u32_e32 v26, v22, v52
	v_add_u32_e32 v22, v22, v53
	v_lshl_or_b32 v21, v56, 6, v1
	s_waitcnt vmcnt(3)
	ds_write_b128 v24, v[200:203]
	s_waitcnt vmcnt(2)
	ds_write_b128 v25, v[204:207]
	s_waitcnt vmcnt(1)
	ds_write_b128 v26, v[208:211]
	s_waitcnt vmcnt(0)
	ds_write_b128 v22, v[212:215]
	s_waitcnt lgkmcnt(0)
	s_barrier
; #define LAS __attribute__((address_space(3)))
; __device__ __forceinline__ void ret_unit_c(PR P, LAS unsigned char* lds, const int bh, const int n, const int wv) {
;     ...
;     f32x4 accY[2][4];
; #pragma unroll
;     for (int mt = 0; mt < 2; ++mt)
; #pragma unroll
;         for (int nt = 0; nt < 4; ++nt) accY[mt][nt] = (f32x4){0.f, 0.f, 0.f, 0.f};
; #pragma unroll
;     for (int ks = 0; ks < 4; ++ks) { bf16x8 aq[2];
; #pragma unroll
;         for (int mt = 0; mt < 2; ++mt) aq[mt] = *(const LAS bf16x8*)(QP + (wr * 32 + mt * 16 + fr) * RS + ks * 32 + fq * 8);
; #pragma unroll
;         for (int nt = 0; nt < 4; ++nt) { const bf16x8 bs = *(const LAS bf16x8*)(ST + (wc * 64 + nt * 16 + fr) * RS + ks * 32 + fq * 8);
; #pragma unroll
;             for (int mt = 0; mt < 2; ++mt) accY[mt][nt] = __builtin_amdgcn_mfma_f32_16x16x32_bf16(aq[mt], bs, accY[mt][nt], 0, 0, 0); }
;         __builtin_amdgcn_sched_barrier(0); }
; #pragma unroll
;     for (int mt = 0; mt < 2; ++mt)
; #pragma unroll
;         for (int j = 0; j < 4; ++j) { const int r = wr * 32 + mt * 16 + fq * 4 + j; const float qd = exp2f(lg2 * (float)(r + 1));
; #pragma unroll
;             for (int nt = 0; nt < 4; ++nt) YST[r * 132 + wc * 64 + nt * 16 + fr] = accY[mt][nt][j] * qd; }
	ds_read_b128 v[4:7], v28
	v_mul_u32_u24_e32 v8, 0x110, v21
	v_add3_u32 v58, s36, v20, v8
	ds_read_b128 v[8:11], v28 offset:4352
	ds_read_b128 v[12:15], v58
	ds_read_b128 v[16:19], v58 offset:4352
	ds_read_b128 v[32:35], v58 offset:8704
	ds_read_b128 v[36:39], v58 offset:13056
	s_waitcnt lgkmcnt(3)
	v_mfma_f32_16x16x32_bf16 v[20:23], v[4:7], v[12:15], 0
	v_mfma_f32_16x16x32_bf16 v[12:15], v[8:11], v[12:15], 0
	s_waitcnt lgkmcnt(2)
	v_mfma_f32_16x16x32_bf16 v[24:27], v[4:7], v[16:19], 0
	v_mfma_f32_16x16x32_bf16 v[16:19], v[8:11], v[16:19], 0
	s_waitcnt lgkmcnt(1)
	v_mfma_f32_16x16x32_bf16 v[40:43], v[4:7], v[32:35], 0
	v_mfma_f32_16x16x32_bf16 v[32:35], v[8:11], v[32:35], 0
	s_waitcnt lgkmcnt(0)
	v_mfma_f32_16x16x32_bf16 v[4:7], v[4:7], v[36:39], 0
	v_mfma_f32_16x16x32_bf16 v[8:11], v[8:11], v[36:39], 0
	ds_read_b128 v[36:39], v28 offset:64
	ds_read_b128 v[44:47], v28 offset:4416
	ds_read_b128 v[48:51], v58 offset:64
	ds_read_b128 v[52:55], v58 offset:4416
	s_waitcnt lgkmcnt(1)
	v_mfma_f32_16x16x32_bf16 v[20:23], v[36:39], v[48:51], v[20:23]
	v_mfma_f32_16x16x32_bf16 v[12:15], v[44:47], v[48:51], v[12:15]
	s_waitcnt lgkmcnt(0)
	v_mfma_f32_16x16x32_bf16 v[24:27], v[36:39], v[52:55], v[24:27]
	v_mfma_f32_16x16x32_bf16 v[16:19], v[44:47], v[52:55], v[16:19]
	ds_read_b128 v[48:51], v58 offset:8768
	ds_read_b128 v[52:55], v58 offset:13120
	s_waitcnt lgkmcnt(1)
	v_mfma_f32_16x16x32_bf16 v[40:43], v[36:39], v[48:51], v[40:43]
	v_mfma_f32_16x16x32_bf16 v[32:35], v[44:47], v[48:51], v[32:35]
	s_waitcnt lgkmcnt(0)
	v_mfma_f32_16x16x32_bf16 v[4:7], v[36:39], v[52:55], v[4:7]
	v_mfma_f32_16x16x32_bf16 v[8:11], v[44:47], v[52:55], v[8:11]
	ds_read_b128 v[36:39], v28 offset:128
	ds_read_b128 v[44:47], v28 offset:4480
	ds_read_b128 v[48:51], v58 offset:128
	ds_read_b128 v[52:55], v58 offset:4480
	s_waitcnt lgkmcnt(1)
	v_mfma_f32_16x16x32_bf16 v[20:23], v[36:39], v[48:51], v[20:23]
	v_mfma_f32_16x16x32_bf16 v[12:15], v[44:47], v[48:51], v[12:15]
	s_waitcnt lgkmcnt(0)
	v_mfma_f32_16x16x32_bf16 v[24:27], v[36:39], v[52:55], v[24:27]
	v_mfma_f32_16x16x32_bf16 v[16:19], v[44:47], v[52:55], v[16:19]
	ds_read_b128 v[48:51], v58 offset:8832
	ds_read_b128 v[52:55], v58 offset:13184
	s_waitcnt lgkmcnt(1)
	v_mfma_f32_16x16x32_bf16 v[40:43], v[36:39], v[48:51], v[40:43]
	v_mfma_f32_16x16x32_bf16 v[32:35], v[44:47], v[48:51], v[32:35]
	s_waitcnt lgkmcnt(0)
	v_mfma_f32_16x16x32_bf16 v[4:7], v[36:39], v[52:55], v[4:7]
	v_mfma_f32_16x16x32_bf16 v[8:11], v[44:47], v[52:55], v[8:11]
	ds_read_b128 v[36:39], v28 offset:192
	ds_read_b128 v[44:47], v28 offset:4544
	ds_read_b128 v[48:51], v58 offset:192
	ds_read_b128 v[52:55], v58 offset:4544
	s_waitcnt lgkmcnt(1)
	v_mfma_f32_16x16x32_bf16 v[20:23], v[36:39], v[48:51], v[20:23]
	v_mfma_f32_16x16x32_bf16 v[12:15], v[44:47], v[48:51], v[12:15]
	s_waitcnt lgkmcnt(0)
	v_mfma_f32_16x16x32_bf16 v[24:27], v[36:39], v[52:55], v[24:27]
	v_mfma_f32_16x16x32_bf16 v[16:19], v[44:47], v[52:55], v[16:19]
	ds_read_b128 v[48:51], v58 offset:8896
	ds_read_b128 v[52:55], v58 offset:13248
	s_waitcnt lgkmcnt(1)
	v_mfma_f32_16x16x32_bf16 v[40:43], v[36:39], v[48:51], v[40:43]
	v_mfma_f32_16x16x32_bf16 v[32:35], v[44:47], v[48:51], v[32:35]
	s_waitcnt lgkmcnt(0)
	v_mfma_f32_16x16x32_bf16 v[4:7], v[36:39], v[52:55], v[4:7]
	v_mfma_f32_16x16x32_bf16 v[8:11], v[44:47], v[52:55], v[8:11]
	v_cmp_gt_f32_e32 vcc, s37, v57
	s_and_b64 s[26:27], vcc, exec
	s_cselect_b32 s26, 32, 0
	v_ldexp_f32 v36, v57, s26
	v_lshl_or_b32 v0, v0, 2, v3
	v_log_f32_e32 v36, v36
	v_or_b32_e32 v3, 1, v0
	v_cvt_f32_i32_e32 v3, v3
	v_cndmask_b32_e32 v28, 0, v63, vcc
	v_sub_f32_e32 v28, v36, v28
	v_lshlrev_b32_e32 v1, 2, v1
	v_mul_f32_e32 v36, v28, v3
	v_cmp_gt_f32_e32 vcc, s30, v36
	v_lshlrev_b32_e32 v2, 5, v2
	s_nop 0
	v_cndmask_b32_e32 v36, 0, v62, vcc
	v_fmac_f32_e32 v36, v28, v3
	v_exp_f32_e32 v3, v36
	v_cndmask_b32_e32 v37, 0, v64, vcc
	v_lshl_add_u32 v36, v56, 8, 0
	v_ldexp_f32 v3, v3, v37
	v_mul_lo_u32 v37, v0, s40
	v_add3_u32 v1, v36, v1, v37
	v_or_b32_e32 v36, 2, v0
	v_cvt_f32_i32_e32 v36, v36
	v_mul_f32_e32 v20, v3, v20
	v_mul_f32_e32 v24, v3, v24
	v_add_u32_e32 v37, 0x8800, v1
	ds_write2_b32 v37, v20, v24 offset1:16
	v_mul_f32_e32 v24, v28, v36
	v_cmp_gt_f32_e32 vcc, s30, v24
	v_mul_f32_e32 v20, v3, v40
	v_mul_f32_e32 v3, v3, v4
	v_cndmask_b32_e32 v24, 0, v62, vcc
	v_fmac_f32_e32 v24, v28, v36
	v_exp_f32_e32 v24, v24
	ds_write2_b32 v37, v20, v3 offset0:32 offset1:48
	v_or_b32_e32 v20, 3, v0
	v_cvt_f32_i32_e32 v20, v20
	v_cndmask_b32_e32 v3, 0, v64, vcc
	v_ldexp_f32 v3, v24, v3
	v_mul_f32_e32 v4, v3, v21
	v_mul_f32_e32 v21, v3, v25
	ds_write2_b32 v37, v4, v21 offset0:132 offset1:148
	v_mul_f32_e32 v21, v28, v20
	v_cmp_gt_f32_e32 vcc, s30, v21
	v_mul_f32_e32 v4, v3, v41
	v_mul_f32_e32 v3, v3, v5
	v_cndmask_b32_e32 v21, 0, v62, vcc
	v_fmac_f32_e32 v21, v28, v20
	v_exp_f32_e32 v20, v21
	ds_write2_b32 v37, v4, v3 offset0:164 offset1:180
	v_cndmask_b32_e32 v3, 0, v64, vcc
	v_add_u32_e32 v21, 0x8c00, v1
	v_ldexp_f32 v3, v20, v3
	v_add_u32_e32 v20, 4, v0
	v_cvt_f32_i32_e32 v20, v20
	v_mul_f32_e32 v4, v3, v22
	v_mul_f32_e32 v5, v3, v26
	ds_write2_b32 v21, v4, v5 offset0:8 offset1:24
	v_mul_f32_e32 v5, v28, v20
	v_cmp_gt_f32_e32 vcc, s30, v5
	v_mul_f32_e32 v4, v3, v42
	v_mul_f32_e32 v3, v3, v6
	v_cndmask_b32_e32 v5, 0, v62, vcc
	v_fmac_f32_e32 v5, v28, v20
	v_exp_f32_e32 v5, v5
	ds_write2_b32 v21, v4, v3 offset0:40 offset1:56
	v_cndmask_b32_e32 v3, 0, v64, vcc
	v_ldexp_f32 v3, v5, v3
	v_or_b32_e32 v5, 17, v0
	v_cvt_f32_i32_e32 v5, v5
	v_mul_f32_e32 v4, v3, v23
	v_mul_f32_e32 v6, v3, v27
	ds_write2_b32 v21, v4, v6 offset0:140 offset1:156
	v_mul_f32_e32 v6, v28, v5
; #define LAS __attribute__((address_space(3)))
; __device__ __forceinline__ float lo_bf(unsigned x) { return __uint_as_float(x << 16); }
; __device__ __forceinline__ float hi_bf(unsigned x) { return __uint_as_float(x & 0xffff0000u); }
; __device__ __forceinline__ float quad_sum(float v) { v += dppf<0xB1>(v); v += dppf<0x4E>(v); return v; }
; __device__ __forceinline__ void ret_unit_c(PR P, LAS unsigned char* lds, const int bh, const int n, const int wv) {
;     ...
;         for (int j = 0; j < 4; ++j) { const int r = wr * 32 + mt * 16 + fq * 4 + j; const float qd = exp2f(lg2 * (float)(r + 1));
; #pragma unroll
;             for (int nt = 0; nt < 4; ++nt) YST[r * 132 + wc * 64 + nt * 16 + fr] = accY[mt][nt][j] * qd; }
;     __syncthreads();
;     { const int i = tid >> 2, part = tid & 3; float yv[32]; float s = 0.f;
;       bf16_t* yo = Y + (size_t)(row0 + i) * 1024 + 512 + h * 128 + part * 32;
; #pragma unroll
;       for (int x = 0; x < 4; ++x) { const u32x4 y1 = *(const u32x4*)(yo + x * 8); const f32x4 ta = *(const LAS f32x4*)(YST + i * 132 + part * 32 + x * 8), tb = *(const LAS f32x4*)(YST + i * 132 + part * 32 + x * 8 + 4);
;           yv[x * 8 + 0] = ta[0] + lo_bf(y1.x); yv[x * 8 + 1] = ta[1] + hi_bf(y1.x); yv[x * 8 + 2] = ta[2] + lo_bf(y1.y); yv[x * 8 + 3] = ta[3] + hi_bf(y1.y);
;           yv[x * 8 + 4] = tb[0] + lo_bf(y1.z); yv[x * 8 + 5] = tb[1] + hi_bf(y1.z); yv[x * 8 + 6] = tb[2] + lo_bf(y1.w); yv[x * 8 + 7] = tb[3] + hi_bf(y1.w); }
; #pragma unroll
;       for (int x = 0; x < 32; ++x) s += yv[x];
;       s = quad_sum(s); const float mean = s * (1.0f / 128.0f); float s2 = 0.f;
; #pragma unroll
;       for (int x = 0; x < 32; ++x) { yv[x] -= mean; s2 += yv[x] * yv[x]; }
;       s2 = quad_sum(s2); const float rstd = rsqrtf(s2 * (1.0f / 128.0f) + 1e-5f);
;       const bf16_t* gp = PS + (size_t)(row0 + i) * NCOLS + 1792 + 1536 + h * 128 + part * 32; const float* gw = P.gn_w + h * 128 + part * 32;
; #pragma unroll
;       for (int x = 0; x < 4; ++x) { const u32x4 g4 = *(const u32x4*)(gp + x * 8); const float4 w0 = *(const float4*)(gw + x * 8), w1 = *(const float4*)(gw + x * 8 + 4);
	v_cmp_gt_f32_e32 vcc, s30, v6
	v_mul_f32_e32 v4, v3, v43
	v_mul_f32_e32 v3, v3, v7
	v_cndmask_b32_e32 v6, 0, v62, vcc
	v_fmac_f32_e32 v6, v28, v5
	v_exp_f32_e32 v5, v6
	v_or_b32_e32 v6, 18, v0
	v_cvt_f32_i32_e32 v6, v6
	ds_write2_b32 v21, v4, v3 offset0:172 offset1:188
	v_cndmask_b32_e32 v3, 0, v64, vcc
	v_ldexp_f32 v3, v5, v3
	v_mul_f32_e32 v4, v3, v12
	v_mul_f32_e32 v5, v3, v16
	v_add_u32_e32 v7, 0xa800, v1
	ds_write2_b32 v7, v4, v5 offset0:64 offset1:80
	v_mul_f32_e32 v5, v28, v6
	v_cmp_gt_f32_e32 vcc, s30, v5
	v_mul_f32_e32 v4, v3, v32
	v_mul_f32_e32 v3, v3, v8
	v_cndmask_b32_e32 v5, 0, v62, vcc
	v_fmac_f32_e32 v5, v28, v6
	v_exp_f32_e32 v5, v5
	ds_write2_b32 v7, v4, v3 offset0:96 offset1:112
	v_cndmask_b32_e32 v3, 0, v64, vcc
	v_add_u32_e32 v1, 0xac00, v1
	v_ldexp_f32 v3, v5, v3
	v_or_b32_e32 v5, 19, v0
	v_cvt_f32_i32_e32 v5, v5
	v_mul_f32_e32 v4, v3, v13
	v_mul_f32_e32 v6, v3, v17
	ds_write2_b32 v7, v4, v6 offset0:196 offset1:212
	v_mul_f32_e32 v6, v28, v5
	v_cmp_gt_f32_e32 vcc, s30, v6
	v_add_u32_e32 v0, 20, v0
	v_mul_f32_e32 v4, v3, v33
	v_cndmask_b32_e32 v6, 0, v62, vcc
	v_fmac_f32_e32 v6, v28, v5
	v_exp_f32_e32 v5, v6
	v_mul_f32_e32 v3, v3, v9
	v_cvt_f32_i32_e32 v0, v0
	ds_write2_b32 v7, v4, v3 offset0:228 offset1:244
	v_cndmask_b32_e32 v3, 0, v64, vcc
	v_ldexp_f32 v3, v5, v3
	v_mul_f32_e32 v4, v3, v14
	v_mul_f32_e32 v5, v3, v18
	ds_write2_b32 v1, v4, v5 offset0:72 offset1:88
	v_mul_f32_e32 v5, v28, v0
	v_cmp_gt_f32_e32 vcc, s30, v5
	v_mul_f32_e32 v4, v3, v34
	v_mul_f32_e32 v3, v3, v10
	v_cndmask_b32_e32 v5, 0, v62, vcc
	v_fmac_f32_e32 v5, v28, v0
	v_exp_f32_e32 v0, v5
	ds_write2_b32 v1, v4, v3 offset0:104 offset1:120
	v_cndmask_b32_e32 v3, 0, v64, vcc
	v_and_b32_e32 v10, 0x60, v2
	v_ldexp_f32 v0, v0, v3
	v_mul_f32_e32 v3, v0, v15
	v_mul_f32_e32 v4, v0, v19
	ds_write2_b32 v1, v3, v4 offset0:204 offset1:220
	v_add_u32_e32 v4, s45, v66
	v_mul_f32_e32 v3, v0, v35
	v_mul_f32_e32 v0, v0, v11
	v_ashrrev_i32_e32 v5, 31, v4
	ds_write2_b32 v1, v3, v0 offset0:236 offset1:252
	v_lshlrev_b64 v[0:1], 11, v[4:5]
	v_lshl_add_u64 v[6:7], s[10:11], 0, v[0:1]
	v_lshl_add_u64 v[0:1], v[6:7], 0, s[18:19]
	v_lshlrev_b32_e32 v28, 1, v10
	v_lshl_add_u64 v[8:9], v[0:1], 0, v[28:29]
	v_mad_i64_i32 v[4:5], s[26:27], v4, s42, v[6:7]
	v_add_co_u32_e32 v34, vcc, s41, v8
	v_lshl_add_u64 v[4:5], v[4:5], 0, s[18:19]
	s_nop 0
	v_addc_co_u32_e32 v35, vcc, 0, v9, vcc
	v_lshl_add_u64 v[12:13], v[4:5], 0, v[28:29]
	v_lshl_add_u64 v[32:33], v[8:9], 0, s[22:23]
	v_add_co_u32_e32 v4, vcc, s43, v12
	s_waitcnt lgkmcnt(0)
	s_barrier
	global_load_dwordx4 v[0:3], v[32:33], off offset:48
	v_addc_co_u32_e32 v5, vcc, 0, v13, vcc
	global_load_dwordx4 v[58:61], v[4:5], off offset:512
	global_load_dwordx4 v[52:55], v[34:35], off offset:3072
	v_mul_lo_u32 v4, v66, s40
	global_load_dwordx4 v[20:23], v[32:33], off offset:32
	global_load_dwordx4 v[66:69], v[32:33], off offset:16
	v_lshlrev_b32_e32 v28, 2, v10
	v_add3_u32 v8, 0, v4, v28
	ds_read_b128 v[70:73], v8 offset:34816
	ds_read_b128 v[44:47], v8 offset:34832
	ds_read_b128 v[74:77], v8 offset:34848
	ds_read_b128 v[78:81], v8 offset:34864
	ds_read_b128 v[4:7], v8 offset:34912
	ds_read_b128 v[24:27], v8 offset:34880
	ds_read_b128 v[82:85], v8 offset:34896
	ds_read_b128 v[8:11], v8 offset:34928
	s_lshl_b32 s18, s44, 9
	s_add_u32 s26, s12, s18
	s_addc_u32 s27, s13, 0
	s_addk_i32 s28, 0x80
	s_cmpk_eq_i32 s28, 0x180
	s_waitcnt vmcnt(4)
	v_and_b32_e32 v15, 0xffff0000, v0
	v_lshlrev_b32_e32 v14, 16, v0
	s_waitcnt lgkmcnt(3)
	v_pk_add_f32 v[40:41], v[4:5], v[14:15]
	v_and_b32_e32 v5, 0xffff0000, v1
	v_lshlrev_b32_e32 v4, 16, v1
	v_and_b32_e32 v1, 0xffff0000, v2
	v_lshlrev_b32_e32 v0, 16, v2
	s_waitcnt vmcnt(3)
	v_lshlrev_b32_e32 v38, 16, v60
	s_waitcnt lgkmcnt(0)
	v_pk_add_f32 v[48:49], v[8:9], v[0:1]
	v_lshl_add_u64 v[8:9], v[12:13], 0, s[24:25]
	s_waitcnt vmcnt(2)
	v_lshlrev_b32_e32 v12, 16, v55
	v_and_b32_e32 v13, 0xffff0000, v55
	v_and_b32_e32 v39, 0xffff0000, v60
	v_mul_f32_e32 v37, 0xbfb8aa3b, v38
	v_pk_add_f32 v[56:57], v[46:47], v[12:13]
	v_exp_f32_e32 v46, v37
	v_mul_f32_e32 v37, 0xbfb8aa3b, v39
	v_exp_f32_e32 v47, v37
	v_lshlrev_b32_e32 v36, 16, v61
	v_add_f32_e32 v46, 1.0, v46
	v_rcp_f32_e32 v46, v46
	v_add_f32_e32 v47, 1.0, v47
	v_rcp_f32_e32 v47, v47
	v_and_b32_e32 v37, 0xffff0000, v61
	v_lshlrev_b32_e32 v60, 16, v54
	v_and_b32_e32 v61, 0xffff0000, v54
	v_pk_add_f32 v[60:61], v[44:45], v[60:61]
	v_lshlrev_b32_e32 v44, 16, v59
	v_and_b32_e32 v45, 0xffff0000, v59
	v_pk_mul_f32 v[38:39], v[46:47], v[38:39]
	v_lshlrev_b32_e32 v46, 16, v53
	v_and_b32_e32 v47, 0xffff0000, v53
	v_mul_f32_e32 v53, 0xbfb8aa3b, v44
	v_mul_f32_e32 v54, 0xbfb8aa3b, v45
	v_exp_f32_e32 v53, v53
	v_exp_f32_e32 v54, v54
	v_pk_add_f32 v[72:73], v[72:73], v[46:47]
	v_and_b32_e32 v55, 0xffff0000, v52
	v_add_f32_e32 v46, 1.0, v53
	v_add_f32_e32 v47, 1.0, v54
	v_lshlrev_b32_e32 v54, 16, v52
	v_lshlrev_b32_e32 v52, 16, v58
	v_and_b32_e32 v53, 0xffff0000, v58
	v_pk_add_f32 v[70:71], v[70:71], v[54:55]
	v_mul_f32_e32 v55, 0xbfb8aa3b, v52
	v_mul_f32_e32 v58, 0xbfb8aa3b, v53
	v_exp_f32_e32 v55, v55
	v_exp_f32_e32 v58, v58
	v_add_f32_e32 v54, 0, v70
	v_add_f32_e32 v59, v71, v54
	v_add_f32_e32 v54, 1.0, v55
	v_add_f32_e32 v55, 1.0, v58
	v_add_f32_e32 v58, v72, v59
	v_mul_f32_e32 v59, 0xbfb8aa3b, v36
	v_mul_f32_e32 v86, 0xbfb8aa3b, v37
	v_add_f32_e32 v58, v73, v58
	v_exp_f32_e32 v59, v59
	v_exp_f32_e32 v86, v86
	v_add_f32_e32 v58, v60, v58
	v_and_b32_e32 v1, 0xffff0000, v3
	v_lshlrev_b32_e32 v0, 16, v3
	v_add_f32_e32 v58, v61, v58
	v_pk_add_f32 v[42:43], v[6:7], v[4:5]
	v_pk_add_f32 v[50:51], v[10:11], v[0:1]
	global_load_dwordx4 v[0:3], v[8:9], off offset:48
	global_load_dwordx4 v[4:7], v[8:9], off offset:32
	s_nop 0
	global_load_dwordx4 v[8:11], v[8:9], off offset:16
	s_nop 0
	s_nop 1
	v_mov_b32_e32 v12, v232
	v_mov_b32_e32 v13, v233
	v_mov_b32_e32 v14, v234
	v_mov_b32_e32 v15, v235
	s_nop 1
	v_mov_b32_e32 v16, v228
	v_mov_b32_e32 v17, v229
	v_mov_b32_e32 v18, v230
	v_mov_b32_e32 v19, v231
	v_add_f32_e32 v58, v56, v58
	v_add_f32_e32 v88, v57, v58
	v_add_f32_e32 v58, 1.0, v59
	v_add_f32_e32 v59, 1.0, v86
	s_waitcnt vmcnt(3)
; #define LAS __attribute__((address_space(3)))
; __device__ __forceinline__ float lo_bf(unsigned x) { return __uint_as_float(x << 16); }
; __device__ __forceinline__ float hi_bf(unsigned x) { return __uint_as_float(x & 0xffff0000u); }
; __device__ __forceinline__ float quad_sum(float v) { v += dppf<0xB1>(v); v += dppf<0x4E>(v); return v; }
; __device__ __forceinline__ void ret_unit_c(PR P, LAS unsigned char* lds, const int bh, const int n, const int wv) {
;     ...
;       for (int x = 0; x < 4; ++x) { const u32x4 y1 = *(const u32x4*)(yo + x * 8); const f32x4 ta = *(const LAS f32x4*)(YST + i * 132 + part * 32 + x * 8), tb = *(const LAS f32x4*)(YST + i * 132 + part * 32 + x * 8 + 4);
;           yv[x * 8 + 0] = ta[0] + lo_bf(y1.x); yv[x * 8 + 1] = ta[1] + hi_bf(y1.x); yv[x * 8 + 2] = ta[2] + lo_bf(y1.y); yv[x * 8 + 3] = ta[3] + hi_bf(y1.y);
;           yv[x * 8 + 4] = tb[0] + lo_bf(y1.z); yv[x * 8 + 5] = tb[1] + hi_bf(y1.z); yv[x * 8 + 6] = tb[2] + lo_bf(y1.w); yv[x * 8 + 7] = tb[3] + hi_bf(y1.w); }
; #pragma unroll
;       for (int x = 0; x < 32; ++x) s += yv[x];
;       s = quad_sum(s); const float mean = s * (1.0f / 128.0f); float s2 = 0.f;
; #pragma unroll
;       for (int x = 0; x < 32; ++x) { yv[x] -= mean; s2 += yv[x] * yv[x]; }
;       s2 = quad_sum(s2); const float rstd = rsqrtf(s2 * (1.0f / 128.0f) + 1e-5f);
	v_lshlrev_b32_e32 v86, 16, v69
	v_and_b32_e32 v87, 0xffff0000, v69
	v_pk_add_f32 v[80:81], v[80:81], v[86:87]
	v_lshlrev_b32_e32 v86, 16, v68
	v_and_b32_e32 v87, 0xffff0000, v68
	v_pk_add_f32 v[68:69], v[78:79], v[86:87]
	v_lshlrev_b32_e32 v78, 16, v67
	v_and_b32_e32 v79, 0xffff0000, v67
	v_pk_add_f32 v[76:77], v[76:77], v[78:79]
	v_lshlrev_b32_e32 v78, 16, v66
	v_and_b32_e32 v79, 0xffff0000, v66
	v_pk_add_f32 v[66:67], v[74:75], v[78:79]
	v_lshlrev_b32_e32 v78, 16, v22
	v_add_f32_e32 v74, v66, v88
	v_add_f32_e32 v74, v67, v74
	v_add_f32_e32 v74, v76, v74
	v_add_f32_e32 v74, v77, v74
	v_add_f32_e32 v74, v68, v74
	v_add_f32_e32 v74, v69, v74
	v_add_f32_e32 v74, v80, v74
	v_and_b32_e32 v79, 0xffff0000, v22
	v_add_f32_e32 v86, v81, v74
	v_lshlrev_b32_e32 v74, 16, v23
	v_and_b32_e32 v75, 0xffff0000, v23
	v_pk_add_f32 v[22:23], v[82:83], v[78:79]
	v_lshlrev_b32_e32 v78, 16, v21
	v_and_b32_e32 v79, 0xffff0000, v21
	v_pk_add_f32 v[26:27], v[26:27], v[78:79]
	v_lshlrev_b32_e32 v78, 16, v20
	v_and_b32_e32 v79, 0xffff0000, v20
	v_pk_add_f32 v[20:21], v[24:25], v[78:79]
	v_pk_add_f32 v[74:75], v[84:85], v[74:75]
	v_add_f32_e32 v24, v20, v86
	v_add_f32_e32 v24, v21, v24
	v_add_f32_e32 v24, v26, v24
	v_add_f32_e32 v24, v27, v24
	v_add_f32_e32 v24, v22, v24
	v_add_f32_e32 v24, v23, v24
	v_add_f32_e32 v24, v74, v24
	v_add_f32_e32 v24, v75, v24
	v_add_f32_e32 v24, v40, v24
	v_add_f32_e32 v24, v41, v24
	v_add_f32_e32 v24, v42, v24
	v_add_f32_e32 v24, v43, v24
	v_add_f32_e32 v24, v48, v24
	v_add_f32_e32 v24, v49, v24
	v_add_f32_e32 v24, v50, v24
	v_add_f32_e32 v24, v51, v24
	v_rcp_f32_e32 v46, v46
	v_rcp_f32_e32 v47, v47
	v_add_f32_dpp v24, v24, v24 quad_perm:[1,0,3,2] row_mask:0xf bank_mask:0xf bound_ctrl:1
	v_rcp_f32_e32 v54, v54
	v_rcp_f32_e32 v55, v55
	v_add_f32_dpp v24, v24, v24 quad_perm:[2,3,0,1] row_mask:0xf bank_mask:0xf bound_ctrl:1
	v_mul_f32_e32 v78, 0x3c000000, v24
	v_pk_add_f32 v[70:71], v[70:71], v[78:79] op_sel_hi:[1,0] neg_lo:[0,1] neg_hi:[0,1]
	v_pk_add_f32 v[72:73], v[72:73], v[78:79] op_sel_hi:[1,0] neg_lo:[0,1] neg_hi:[0,1]
	v_pk_mul_f32 v[82:83], v[70:71], v[70:71]
	v_pk_mul_f32 v[84:85], v[72:73], v[72:73]
	v_add_f32_e32 v82, v82, v83
	v_pk_add_f32 v[60:61], v[60:61], v[78:79] op_sel_hi:[1,0] neg_lo:[0,1] neg_hi:[0,1]
	v_add_f32_e32 v82, v84, v82
	v_pk_mul_f32 v[86:87], v[60:61], v[60:61]
	v_add_f32_e32 v82, v85, v82
	v_pk_add_f32 v[56:57], v[56:57], v[78:79] op_sel_hi:[1,0] neg_lo:[0,1] neg_hi:[0,1]
	v_add_f32_e32 v82, v86, v82
	v_pk_mul_f32 v[88:89], v[56:57], v[56:57]
	v_add_f32_e32 v82, v87, v82
	v_pk_add_f32 v[66:67], v[66:67], v[78:79] op_sel_hi:[1,0] neg_lo:[0,1] neg_hi:[0,1]
	v_add_f32_e32 v82, v88, v82
	v_pk_mul_f32 v[90:91], v[66:67], v[66:67]
	v_add_f32_e32 v82, v89, v82
	v_pk_add_f32 v[76:77], v[76:77], v[78:79] op_sel_hi:[1,0] neg_lo:[0,1] neg_hi:[0,1]
	v_add_f32_e32 v82, v90, v82
	v_pk_mul_f32 v[92:93], v[76:77], v[76:77]
	v_add_f32_e32 v82, v91, v82
	v_pk_add_f32 v[68:69], v[68:69], v[78:79] op_sel_hi:[1,0] neg_lo:[0,1] neg_hi:[0,1]
	v_add_f32_e32 v82, v92, v82
	v_pk_mul_f32 v[94:95], v[68:69], v[68:69]
	v_add_f32_e32 v82, v93, v82
	v_pk_add_f32 v[80:81], v[80:81], v[78:79] op_sel_hi:[1,0] neg_lo:[0,1] neg_hi:[0,1]
	v_add_f32_e32 v82, v94, v82
	v_pk_mul_f32 v[96:97], v[80:81], v[80:81]
	v_add_f32_e32 v82, v95, v82
	v_pk_add_f32 v[98:99], v[20:21], v[78:79] op_sel_hi:[1,0] neg_lo:[0,1] neg_hi:[0,1]
	v_add_f32_e32 v82, v96, v82
	v_pk_mul_f32 v[100:101], v[98:99], v[98:99]
	v_add_f32_e32 v82, v97, v82
	v_pk_add_f32 v[26:27], v[26:27], v[78:79] op_sel_hi:[1,0] neg_lo:[0,1] neg_hi:[0,1]
	v_add_f32_e32 v82, v100, v82
	v_pk_mul_f32 v[102:103], v[26:27], v[26:27]
	v_add_f32_e32 v82, v101, v82
	v_pk_add_f32 v[104:105], v[22:23], v[78:79] op_sel_hi:[1,0] neg_lo:[0,1] neg_hi:[0,1]
	v_add_f32_e32 v82, v102, v82
	v_pk_mul_f32 v[106:107], v[104:105], v[104:105]
	v_add_f32_e32 v82, v103, v82
	v_pk_add_f32 v[74:75], v[74:75], v[78:79] op_sel_hi:[1,0] neg_lo:[0,1] neg_hi:[0,1]
	v_add_f32_e32 v82, v106, v82
	v_pk_mul_f32 v[108:109], v[74:75], v[74:75]
	v_add_f32_e32 v82, v107, v82
	v_pk_add_f32 v[40:41], v[40:41], v[78:79] op_sel_hi:[1,0] neg_lo:[0,1] neg_hi:[0,1]
	v_add_f32_e32 v82, v108, v82
	v_pk_add_f32 v[22:23], v[48:49], v[78:79] op_sel_hi:[1,0] neg_lo:[0,1] neg_hi:[0,1]
	v_pk_add_f32 v[20:21], v[50:51], v[78:79] op_sel_hi:[1,0] neg_lo:[0,1] neg_hi:[0,1]
	v_pk_add_f32 v[24:25], v[42:43], v[78:79] op_sel_hi:[1,0] neg_lo:[0,1] neg_hi:[0,1]
	v_pk_mul_f32 v[78:79], v[40:41], v[40:41]
	v_add_f32_e32 v82, v109, v82
	v_add_f32_e32 v78, v78, v82
	v_pk_mul_f32 v[42:43], v[24:25], v[24:25]
	v_add_f32_e32 v78, v79, v78
	v_add_f32_e32 v42, v42, v78
	v_pk_mul_f32 v[48:49], v[22:23], v[22:23]
	v_add_f32_e32 v42, v43, v42
	v_add_f32_e32 v42, v48, v42
	v_pk_mul_f32 v[50:51], v[20:21], v[20:21]
	v_add_f32_e32 v42, v49, v42
	v_add_f32_e32 v42, v50, v42
	v_add_f32_e32 v42, v51, v42
	v_rcp_f32_e32 v58, v58
	v_rcp_f32_e32 v59, v59
	v_add_f32_dpp v42, v42, v42 quad_perm:[1,0,3,2] row_mask:0xf bank_mask:0xf bound_ctrl:1
	v_pk_mul_f32 v[36:37], v[58:59], v[36:37]
	s_nop 0
	v_add_f32_dpp v42, v42, v42 quad_perm:[2,3,0,1] row_mask:0xf bank_mask:0xf bound_ctrl:1
	v_fmamk_f32 v42, v42, 0x3c000000, v65
	v_mul_f32_e32 v43, 0x4b800000, v42
	v_cmp_gt_f32_e32 vcc, s37, v42
	s_nop 1
	v_cndmask_b32_e32 v42, v42, v43, vcc
	v_rsq_f32_e32 v48, v42
	v_pk_mul_f32 v[42:43], v[46:47], v[44:45]
	v_pk_mul_f32 v[44:45], v[54:55], v[52:53]
	v_mul_f32_e32 v46, 0x45800000, v48
	v_cndmask_b32_e32 v46, v48, v46, vcc
	v_pk_mul_f32 v[48:49], v[70:71], v[46:47] op_sel_hi:[1,0]
	s_waitcnt vmcnt(0)
; __device__ __forceinline__ unsigned cvt_pk_bf16(float lo, float hi) { const f32x2_t v = {lo, hi}; const bf16x2_t b = __builtin_convertvector(v, bf16x2_t); return __builtin_bit_cast(unsigned, b); }
; __device__ __forceinline__ float lo_bf(unsigned x) { return __uint_as_float(x << 16); }
; __device__ __forceinline__ float hi_bf(unsigned x) { return __uint_as_float(x & 0xffff0000u); }
; __device__ __forceinline__ void ret_unit_c(PR P, LAS unsigned char* lds, const int bh, const int n, const int wv) {
;     ...
;       const bf16_t* gp = PS + (size_t)(row0 + i) * NCOLS + 1792 + 1536 + h * 128 + part * 32; const float* gw = P.gn_w + h * 128 + part * 32;
; #pragma unroll
;       for (int x = 0; x < 4; ++x) { const u32x4 g4 = *(const u32x4*)(gp + x * 8); const float4 w0 = *(const float4*)(gw + x * 8), w1 = *(const float4*)(gw + x * 8 + 4);
;           const float gg[8] = {lo_bf(g4.x), hi_bf(g4.x), lo_bf(g4.y), hi_bf(g4.y), lo_bf(g4.z), hi_bf(g4.z), lo_bf(g4.w), hi_bf(g4.w)}; const float ww[8] = {w0.x, w0.y, w0.z, w0.w, w1.x, w1.y, w1.z, w1.w};
;           float o[8];
; #pragma unroll
;           for (int z = 0; z < 8; ++z) o[z] = yv[x * 8 + z] * rstd * ww[z] * (gg[z] * __builtin_amdgcn_rcpf(1.0f + __expf(-gg[z])));
;           u32x4 w; w.x = pg8::cvt_pk_bf16(o[0], o[1]); w.y = pg8::cvt_pk_bf16(o[2], o[3]); w.z = pg8::cvt_pk_bf16(o[4], o[5]); w.w = pg8::cvt_pk_bf16(o[6], o[7]);
;           *(u32x4*)(yo + x * 8) = w; } }
	v_pk_mul_f32 v[16:17], v[16:17], v[48:49]
	s_nop 0
	v_pk_mul_f32 v[16:17], v[44:45], v[16:17]
	v_pk_mul_f32 v[44:45], v[72:73], v[46:47] op_sel_hi:[1,0]
	s_nop 0
	v_pk_mul_f32 v[18:19], v[18:19], v[44:45]
	v_and_b32_e32 v45, 0xffff0000, v8
	v_pk_mul_f32 v[18:19], v[42:43], v[18:19]
	v_pk_mul_f32 v[42:43], v[60:61], v[46:47] op_sel_hi:[1,0]
	v_lshlrev_b32_e32 v44, 16, v8
	v_pk_mul_f32 v[12:13], v[12:13], v[42:43]
	v_mul_f32_e32 v8, 0xbfb8aa3b, v44
	v_pk_mul_f32 v[38:39], v[38:39], v[12:13]
	v_pk_mul_f32 v[12:13], v[56:57], v[46:47] op_sel_hi:[1,0]
	v_exp_f32_e32 v8, v8
	v_pk_mul_f32 v[12:13], v[14:15], v[12:13]
	v_cvt_pk_bf16_f32 v14, v38, v39
	v_pk_mul_f32 v[36:37], v[36:37], v[12:13]
	v_cvt_pk_bf16_f32 v12, v16, v17
	v_cvt_pk_bf16_f32 v13, v18, v19
	v_cvt_pk_bf16_f32 v15, v36, v37
	global_store_dwordx4 v[34:35], v[12:15], off offset:3072
	s_nop 1
	v_mov_b32_e32 v12, v236
	v_mov_b32_e32 v13, v237
	v_mov_b32_e32 v14, v238
	v_mov_b32_e32 v15, v239
	s_nop 0
	s_nop 1
	v_mov_b32_e32 v16, v240
	v_mov_b32_e32 v17, v241
	v_mov_b32_e32 v18, v242
	v_mov_b32_e32 v19, v243
	v_and_b32_e32 v37, 0xffff0000, v10
	v_mul_f32_e32 v35, 0xbfb8aa3b, v37
	v_exp_f32_e32 v38, v35
	v_lshlrev_b32_e32 v34, 16, v11
	v_and_b32_e32 v35, 0xffff0000, v11
	v_and_b32_e32 v39, 0xffff0000, v9
	v_add_f32_e32 v11, 1.0, v38
	v_lshlrev_b32_e32 v38, 16, v9
	v_mul_f32_e32 v9, 0xbfb8aa3b, v38
	v_exp_f32_e32 v9, v9
	v_mul_f32_e32 v42, 0xbfb8aa3b, v39
	v_exp_f32_e32 v43, v42
	v_lshlrev_b32_e32 v36, 16, v10
	v_add_f32_e32 v9, 1.0, v9
	v_rcp_f32_e32 v42, v9
	v_add_f32_e32 v9, 1.0, v43
	v_mul_f32_e32 v43, 0xbfb8aa3b, v45
	v_exp_f32_e32 v47, v43
	v_mul_f32_e32 v10, 0xbfb8aa3b, v36
	v_exp_f32_e32 v10, v10
	v_rcp_f32_e32 v43, v9
	v_add_f32_e32 v9, 1.0, v47
	v_mul_f32_e32 v47, 0xbfb8aa3b, v34
	v_exp_f32_e32 v47, v47
	v_mul_f32_e32 v48, 0xbfb8aa3b, v35
	v_add_f32_e32 v10, 1.0, v10
	v_exp_f32_e32 v49, v48
	v_rcp_f32_e32 v10, v10
	v_rcp_f32_e32 v11, v11
	v_add_f32_e32 v8, 1.0, v8
	v_rcp_f32_e32 v8, v8
	v_rcp_f32_e32 v9, v9
	v_add_f32_e32 v47, 1.0, v47
	v_rcp_f32_e32 v48, v47
	v_add_f32_e32 v47, 1.0, v49
	v_pk_mul_f32 v[10:11], v[10:11], v[36:37]
	v_pk_mul_f32 v[36:37], v[42:43], v[38:39]
	v_pk_mul_f32 v[38:39], v[66:67], v[46:47] op_sel_hi:[1,0]
	v_pk_mul_f32 v[8:9], v[8:9], v[44:45]
	v_rcp_f32_e32 v49, v47
	v_pk_mul_f32 v[12:13], v[12:13], v[38:39]
	s_nop 0
	v_pk_mul_f32 v[8:9], v[8:9], v[12:13]
	v_pk_mul_f32 v[12:13], v[76:77], v[46:47] op_sel_hi:[1,0]
	v_pk_mul_f32 v[34:35], v[48:49], v[34:35]
	v_pk_mul_f32 v[12:13], v[14:15], v[12:13]
	v_pk_mul_f32 v[14:15], v[68:69], v[46:47] op_sel_hi:[1,0]
	v_pk_mul_f32 v[12:13], v[36:37], v[12:13]
	v_pk_mul_f32 v[14:15], v[16:17], v[14:15]
	v_cvt_pk_bf16_f32 v8, v8, v9
	v_pk_mul_f32 v[10:11], v[10:11], v[14:15]
	v_pk_mul_f32 v[14:15], v[80:81], v[46:47] op_sel_hi:[1,0]
	v_cvt_pk_bf16_f32 v9, v12, v13
	v_pk_mul_f32 v[14:15], v[18:19], v[14:15]
	v_cvt_pk_bf16_f32 v10, v10, v11
	v_pk_mul_f32 v[14:15], v[34:35], v[14:15]
	v_and_b32_e32 v19, 0xffff0000, v6
	v_cvt_pk_bf16_f32 v11, v14, v15
	global_store_dwordx4 v[32:33], v[8:11], off offset:16
	s_nop 1
	v_mov_b32_e32 v8, v244
	v_mov_b32_e32 v9, v245
	v_mov_b32_e32 v10, v246
	v_mov_b32_e32 v11, v247
	s_nop 0
	s_nop 1
	v_mov_b32_e32 v12, v248
	v_mov_b32_e32 v13, v249
	v_mov_b32_e32 v14, v250
	v_mov_b32_e32 v15, v251
	v_mul_f32_e32 v17, 0xbfb8aa3b, v19
	v_exp_f32_e32 v34, v17
	v_lshlrev_b32_e32 v16, 16, v7
	v_and_b32_e32 v17, 0xffff0000, v7
	v_and_b32_e32 v35, 0xffff0000, v5
	v_add_f32_e32 v7, 1.0, v34
	v_lshlrev_b32_e32 v34, 16, v5
	v_mul_f32_e32 v5, 0xbfb8aa3b, v34
	v_exp_f32_e32 v5, v5
	v_mul_f32_e32 v36, 0xbfb8aa3b, v35
	v_exp_f32_e32 v37, v36
	v_lshlrev_b32_e32 v18, 16, v6
	v_mul_f32_e32 v6, 0xbfb8aa3b, v18
	v_add_f32_e32 v5, 1.0, v5
	v_lshlrev_b32_e32 v38, 16, v4
	v_and_b32_e32 v39, 0xffff0000, v4
	v_exp_f32_e32 v6, v6
	v_rcp_f32_e32 v36, v5
	v_add_f32_e32 v5, 1.0, v37
	v_mul_f32_e32 v4, 0xbfb8aa3b, v38
	v_mul_f32_e32 v37, 0xbfb8aa3b, v39
	v_exp_f32_e32 v4, v4
	v_exp_f32_e32 v42, v37
	v_add_f32_e32 v6, 1.0, v6
	v_rcp_f32_e32 v6, v6
	v_rcp_f32_e32 v7, v7
	v_rcp_f32_e32 v37, v5
	v_add_f32_e32 v4, 1.0, v4
	v_add_f32_e32 v5, 1.0, v42
	v_mul_f32_e32 v42, 0xbfb8aa3b, v16
	v_mul_f32_e32 v43, 0xbfb8aa3b, v17
	v_rcp_f32_e32 v4, v4
	v_exp_f32_e32 v42, v42
	v_exp_f32_e32 v43, v43
	v_rcp_f32_e32 v5, v5
	v_pk_mul_f32 v[6:7], v[6:7], v[18:19]
	v_pk_mul_f32 v[18:19], v[36:37], v[34:35]
	v_pk_mul_f32 v[34:35], v[98:99], v[46:47] op_sel_hi:[1,0]
	v_add_f32_e32 v42, 1.0, v42
	v_add_f32_e32 v43, 1.0, v43
	v_pk_mul_f32 v[4:5], v[4:5], v[38:39]
	v_rcp_f32_e32 v42, v42
	v_rcp_f32_e32 v43, v43
	v_pk_mul_f32 v[8:9], v[8:9], v[34:35]
	s_nop 0
	v_pk_mul_f32 v[4:5], v[4:5], v[8:9]
	v_pk_mul_f32 v[8:9], v[26:27], v[46:47] op_sel_hi:[1,0]
	v_pk_mul_f32 v[16:17], v[42:43], v[16:17]
	v_pk_mul_f32 v[8:9], v[10:11], v[8:9]
	v_pk_mul_f32 v[10:11], v[104:105], v[46:47] op_sel_hi:[1,0]
	v_pk_mul_f32 v[8:9], v[18:19], v[8:9]
	v_pk_mul_f32 v[10:11], v[12:13], v[10:11]
	v_cvt_pk_bf16_f32 v4, v4, v5
	v_pk_mul_f32 v[6:7], v[6:7], v[10:11]
	v_pk_mul_f32 v[10:11], v[74:75], v[46:47] op_sel_hi:[1,0]
	v_cvt_pk_bf16_f32 v5, v8, v9
; __device__ __forceinline__ unsigned cvt_pk_bf16(float lo, float hi) { const f32x2_t v = {lo, hi}; const bf16x2_t b = __builtin_convertvector(v, bf16x2_t); return __builtin_bit_cast(unsigned, b); }
; __device__ __forceinline__ float lo_bf(unsigned x) { return __uint_as_float(x << 16); }
; __device__ __forceinline__ float hi_bf(unsigned x) { return __uint_as_float(x & 0xffff0000u); }
; __device__ __forceinline__ void ret_unit_c(PR P, LAS unsigned char* lds, const int bh, const int n, const int wv) {
;     ...
;       const bf16_t* gp = PS + (size_t)(row0 + i) * NCOLS + 1792 + 1536 + h * 128 + part * 32; const float* gw = P.gn_w + h * 128 + part * 32;
; #pragma unroll
;       for (int x = 0; x < 4; ++x) { const u32x4 g4 = *(const u32x4*)(gp + x * 8); const float4 w0 = *(const float4*)(gw + x * 8), w1 = *(const float4*)(gw + x * 8 + 4);
;           const float gg[8] = {lo_bf(g4.x), hi_bf(g4.x), lo_bf(g4.y), hi_bf(g4.y), lo_bf(g4.z), hi_bf(g4.z), lo_bf(g4.w), hi_bf(g4.w)}; const float ww[8] = {w0.x, w0.y, w0.z, w0.w, w1.x, w1.y, w1.z, w1.w};
;           float o[8];
; #pragma unroll
;           for (int z = 0; z < 8; ++z) o[z] = yv[x * 8 + z] * rstd * ww[z] * (gg[z] * __builtin_amdgcn_rcpf(1.0f + __expf(-gg[z])));
;           u32x4 w; w.x = pg8::cvt_pk_bf16(o[0], o[1]); w.y = pg8::cvt_pk_bf16(o[2], o[3]); w.z = pg8::cvt_pk_bf16(o[4], o[5]); w.w = pg8::cvt_pk_bf16(o[6], o[7]);
;           *(u32x4*)(yo + x * 8) = w; } }
; __global__ void __launch_bounds__(512, 2) hymba_mega(Params P_unused) {
;     ...
;         for (int u = ob; u < 2560; u += 128) { if (u < 2048) rwkv_unit<true>(P, ldsf, u >> 4, (u >> 1) & 7, u & 1, wv); else ret_sample_unit(P, ldsf, (u - 2048) >> 2, (u - 2048) & 3, wv); }
	v_pk_mul_f32 v[10:11], v[14:15], v[10:11]
	v_cvt_pk_bf16_f32 v6, v6, v7
	v_pk_mul_f32 v[10:11], v[16:17], v[10:11]
	v_lshlrev_b32_e32 v12, 16, v0
	v_cvt_pk_bf16_f32 v7, v10, v11
	global_store_dwordx4 v[32:33], v[4:7], off offset:32
	s_nop 1
	v_mov_b32_e32 v4, v192
	v_mov_b32_e32 v5, v193
	v_mov_b32_e32 v6, v194
	v_mov_b32_e32 v7, v195
	s_nop 0
	s_nop 1
	v_mov_b32_e32 v8, v196
	v_mov_b32_e32 v9, v197
	v_mov_b32_e32 v10, v198
	v_mov_b32_e32 v11, v199
	v_and_b32_e32 v13, 0xffff0000, v0
	v_mul_f32_e32 v0, 0xbfb8aa3b, v12
	v_exp_f32_e32 v0, v0
	v_mul_f32_e32 v14, 0xbfb8aa3b, v13
	v_exp_f32_e32 v15, v14
	v_add_f32_e32 v0, 1.0, v0
	v_rcp_f32_e32 v14, v0
	v_add_f32_e32 v0, 1.0, v15
	v_rcp_f32_e32 v15, v0
	v_lshlrev_b32_e32 v0, 16, v1
	v_and_b32_e32 v1, 0xffff0000, v1
	v_pk_mul_f32 v[12:13], v[14:15], v[12:13]
	v_mul_f32_e32 v14, 0xbfb8aa3b, v0
	v_exp_f32_e32 v16, v14
	v_pk_mul_f32 v[14:15], v[40:41], v[46:47] op_sel_hi:[1,0]
	v_pk_mul_f32 v[4:5], v[4:5], v[14:15]
	s_nop 0
	v_pk_mul_f32 v[4:5], v[12:13], v[4:5]
	v_mul_f32_e32 v13, 0xbfb8aa3b, v1
	v_exp_f32_e32 v13, v13
	v_add_f32_e32 v12, 1.0, v16
	v_rcp_f32_e32 v12, v12
	v_pk_mul_f32 v[14:15], v[24:25], v[46:47] op_sel_hi:[1,0]
	v_add_f32_e32 v13, 1.0, v13
	v_rcp_f32_e32 v13, v13
	v_pk_mul_f32 v[6:7], v[6:7], v[14:15]
	v_lshlrev_b32_e32 v14, 16, v2
	v_mul_f32_e32 v15, 0xbfb8aa3b, v14
	v_exp_f32_e32 v16, v15
	v_pk_mul_f32 v[0:1], v[12:13], v[0:1]
	v_and_b32_e32 v15, 0xffff0000, v2
	v_pk_mul_f32 v[6:7], v[0:1], v[6:7]
	v_mul_f32_e32 v1, 0xbfb8aa3b, v15
	v_exp_f32_e32 v1, v1
	v_pk_mul_f32 v[12:13], v[22:23], v[46:47] op_sel_hi:[1,0]
	v_lshlrev_b32_e32 v2, 16, v3
	v_and_b32_e32 v3, 0xffff0000, v3
	v_pk_mul_f32 v[8:9], v[8:9], v[12:13]
	v_mul_f32_e32 v12, 0xbfb8aa3b, v2
	v_mul_f32_e32 v13, 0xbfb8aa3b, v3
	v_exp_f32_e32 v12, v12
	v_exp_f32_e32 v13, v13
	v_add_f32_e32 v0, 1.0, v16
	v_add_f32_e32 v1, 1.0, v1
	v_rcp_f32_e32 v0, v0
	v_rcp_f32_e32 v1, v1
	v_add_f32_e32 v12, 1.0, v12
	v_add_f32_e32 v13, 1.0, v13
	v_rcp_f32_e32 v12, v12
	v_rcp_f32_e32 v13, v13
	v_pk_mul_f32 v[0:1], v[0:1], v[14:15]
	v_pk_mul_f32 v[2:3], v[12:13], v[2:3]
	v_pk_mul_f32 v[8:9], v[0:1], v[8:9]
	v_pk_mul_f32 v[0:1], v[20:21], v[46:47] op_sel_hi:[1,0]
	s_nop 0
	v_pk_mul_f32 v[0:1], v[10:11], v[0:1]
	s_nop 0
	v_pk_mul_f32 v[10:11], v[2:3], v[0:1]
	v_cvt_pk_bf16_f32 v0, v4, v5
	v_cvt_pk_bf16_f32 v1, v6, v7
	v_cvt_pk_bf16_f32 v2, v8, v9
	v_cvt_pk_bf16_f32 v3, v10, v11
	global_store_dwordx4 v[32:33], v[0:3], off offset:48
	s_barrier
	s_cbranch_scc0 .LBB0_654
	s_cmpk_gt_i32 s2, 0xa7f
	s_cbranch_scc1 .LBB0_689
	s_add_u32 s18, s10, 0x3d44800
	s_addc_u32 s19, s11, 0
	s_add_u32 s6, s8, 0x5588000
	s_addc_u32 s7, s9, 0
	s_add_u32 s20, s10, 0xea84800
	s_addc_u32 s21, s11, 0
	s_add_u32 s22, s10, 0xda04800
	s_addc_u32 s23, s11, 0
	s_add_u32 s24, s10, 0xbae4800
	s_addc_u32 s25, s11, 0
	s_add_u32 s26, s8, 0x4588000
	s_addc_u32 s27, s9, 0
	s_and_b32 s44, s2, 3
	v_cvt_f32_ubyte0_e32 v0, s44
	v_sub_f32_e32 v0, 0xc0a00000, v0
	s_mov_b32 s45, 0xc2fc0000
	v_mov_b32_e32 v72, 0x42800000
	v_cmp_gt_f32_e32 vcc, s45, v0
	s_and_b64 s[8:9], vcc, exec
	s_cselect_b32 s8, 0xffffffc0, 0
	v_cndmask_b32_e32 v1, 0, v72, vcc
	v_add_f32_e32 v0, v0, v1
	v_exp_f32_e32 v0, v0
	s_mov_b32 s46, 0x800000
	v_mov_b32_e32 v1, 0x42000000
	s_mov_b32 s29, 0
	v_ldexp_f32 v0, v0, s8
	v_sub_f32_e32 v0, 1.0, v0
	v_cmp_gt_f32_e32 vcc, s46, v0
	s_and_b64 s[8:9], vcc, exec
	s_cselect_b32 s8, 32, 0
	v_ldexp_f32 v0, v0, s8
	v_log_f32_e32 v0, v0
	v_cndmask_b32_e32 v1, 0, v1, vcc
	s_lshl_b32 s47, s44, 7
	s_movk_i32 s57, 0xf00
	v_sub_f32_e32 v73, v0, v1
	v_add_f32_e32 v2, v73, v73
	v_cmp_gt_f32_e32 vcc, s45, v2
	v_mul_f32_e32 v0, 4.0, v73
	s_and_b64 s[8:9], vcc, exec
	v_cndmask_b32_e32 v2, 0, v72, vcc
	v_fmac_f32_e32 v2, 2.0, v73
	v_cmp_gt_f32_e32 vcc, s45, v0
	v_exp_f32_e32 v2, v2
	s_cselect_b32 s8, 0xffffffc0, 0
	v_cndmask_b32_e32 v0, 0, v72, vcc
	v_fmac_f32_e32 v0, 4.0, v73
	v_exp_f32_e32 v0, v0
	v_mul_f32_e32 v1, 0x40400000, v73
	v_ldexp_f32 v74, v2, s8
	s_and_b64 s[8:9], vcc, exec
	s_cselect_b32 s8, 0xffffffc0, 0
	v_cmp_gt_f32_e32 vcc, s45, v1
	v_ldexp_f32 v75, v0, s8
	s_and_b64 s[8:9], vcc, exec
	v_cndmask_b32_e32 v0, 0, v72, vcc
	v_fmac_f32_e32 v0, 0x40400000, v73
	v_cmp_gt_f32_e32 vcc, s45, v73
	v_exp_f32_e32 v0, v0
	s_cselect_b32 s8, 0xffffffc0, 0
	v_cndmask_b32_e32 v1, 0, v72, vcc
	v_add_f32_e32 v1, v73, v1
	v_exp_f32_e32 v1, v1
	v_ldexp_f32 v76, v0, s8
	s_and_b64 s[8:9], vcc, exec
	s_cselect_b32 s8, 0xffffffc0, 0
	v_ldexp_f32 v77, v1, s8
	s_lshl_b32 s8, s44, 8
	s_add_u32 s30, s4, s8
	s_addc_u32 s31, s5, 0
	s_add_u32 s34, s18, s8
	s_addc_u32 s35, s19, 0
	s_lshr_b32 s8, s49, 4
	s_add_i32 s4, s8, 0x4200
	s_lshl_b32 s5, s8, 9
	s_lshl_b32 s9, s2, 5
	s_lshl_b32 s8, s8, 2
	s_add_i32 s55, s9, 0xfffff000
	s_add_i32 s56, s8, 0x4010
	v_mov_b32_e32 v25, 0
	s_movk_i32 s60, 0xff
	s_mov_b64 s[36:37], 0xe00
	s_movk_i32 s61, 0xff90
	s_movk_i32 s62, 0x1e00
	s_movk_i32 s63, 0x1000
	v_mov_b32_e32 v78, 0x3727c5ac
	s_movk_i32 s64, 0x7fff
	s_movk_i32 s65, 0x600
	v_mov_b32_e32 v79, 0x80000
	v_not_b32_e32 v80, 63
	v_mov_b32_e32 v81, 0xffffe000
	s_branch .LBB0_659
